# post-MFMA barrier 4 MFMAs early with priority-2 tail in P1/P5/P6 loops; attention seam wait; peeled first K-iteration; epilogue row-scale prefetch
# speedup vs baseline: 1.0016x; 1.0016x over previous
.LBB0_182:
	s_add_u32 s30, s28, 0x100
	s_addc_u32 s31, s29, 0
	s_cmp_eq_u32 s67, 28
	s_cselect_b32 s42, s7, s30
	s_cselect_b32 s43, s5, s31
	s_cselect_b32 s45, s19, s66
	s_cselect_b32 s44, s21, s61
	s_add_u32 s34, s42, 0x80
	s_addc_u32 s35, s43, 0
	s_add_u32 s36, s44, 0x80
	s_addc_u32 s37, s45, 0
	s_add_u32 s68, s28, 0x80080
	s_addc_u32 s69, s29, 0
	s_add_u32 s40, s42, 0x80000
	s_addc_u32 s41, s43, 0
	s_add_u32 s46, s44, 0x80000
	s_addc_u32 s47, s45, 0
	s_add_u32 s28, s44, 0x80080
	s_addc_u32 s29, s45, 0
	ds_read_b128 v[140:143], v133
	ds_read_b128 v[144:147], v133 offset:1024
	ds_read_b128 v[148:151], v133 offset:2048
	ds_read_b128 v[152:155], v133 offset:3072
	ds_read_b128 v[156:159], v135
	ds_read_b128 v[160:163], v135 offset:1024
	ds_read_b128 v[168:171], v135 offset:2048
	ds_read_b128 v[172:175], v135 offset:3072
	s_add_i32 m0, s38, 0xc000
	ds_read_b128 v[176:179], v164
	ds_read_b128 v[180:183], v164 offset:1024
	ds_read_b128 v[184:187], v164 offset:2048
	ds_read_b128 v[188:191], v164 offset:3072
	ds_read_b128 v[192:195], v164 offset:4096
	ds_read_b128 v[196:199], v164 offset:5120
	ds_read_b128 v[200:203], v164 offset:6144
	ds_read_b128 v[204:207], v164 offset:7168
	global_load_lds_dwordx4 v128, s[68:69]
	s_add_i32 m0, s38, 0xe000
	s_nop 0
	global_load_lds_dwordx4 v132, s[68:69]
	s_waitcnt vmcnt(8)
	s_waitcnt lgkmcnt(0)
	s_barrier
	s_setprio 1
	s_waitcnt lgkmcnt(0)
	v_mfma_f32_16x16x32_bf16 v[124:127], v[140:143], v[176:179], v[124:127]
	v_mfma_f32_16x16x32_bf16 v[120:123], v[148:151], v[176:179], v[120:123]
	v_mfma_f32_16x16x32_bf16 v[108:111], v[140:143], v[184:187], v[108:111]
	v_mfma_f32_16x16x32_bf16 v[104:107], v[148:151], v[184:187], v[104:107]
	v_mfma_f32_16x16x32_bf16 v[92:95], v[140:143], v[192:195], v[92:95]
	v_mfma_f32_16x16x32_bf16 v[88:91], v[148:151], v[192:195], v[88:91]
	v_mfma_f32_16x16x32_bf16 v[76:79], v[140:143], v[200:203], v[76:79]
	v_mfma_f32_16x16x32_bf16 v[72:75], v[148:151], v[200:203], v[72:75]
	v_mfma_f32_16x16x32_bf16 v[124:127], v[144:147], v[180:183], v[124:127]
	v_mfma_f32_16x16x32_bf16 v[120:123], v[152:155], v[180:183], v[120:123]
	v_mfma_f32_16x16x32_bf16 v[108:111], v[144:147], v[188:191], v[108:111]
	v_mfma_f32_16x16x32_bf16 v[104:107], v[152:155], v[188:191], v[104:107]
	v_mfma_f32_16x16x32_bf16 v[92:95], v[144:147], v[196:199], v[92:95]
	v_mfma_f32_16x16x32_bf16 v[88:91], v[152:155], v[196:199], v[88:91]
	v_mfma_f32_16x16x32_bf16 v[76:79], v[144:147], v[204:207], v[76:79]
	v_mfma_f32_16x16x32_bf16 v[72:75], v[152:155], v[204:207], v[72:75]
	s_setprio 0
	s_setprio 1
	v_mfma_f32_16x16x32_bf16 v[116:119], v[156:159], v[176:179], v[116:119]
	v_mfma_f32_16x16x32_bf16 v[112:115], v[168:171], v[176:179], v[112:115]
	v_mfma_f32_16x16x32_bf16 v[100:103], v[156:159], v[184:187], v[100:103]
	v_mfma_f32_16x16x32_bf16 v[96:99], v[168:171], v[184:187], v[96:99]
	v_mfma_f32_16x16x32_bf16 v[84:87], v[156:159], v[192:195], v[84:87]
	v_mfma_f32_16x16x32_bf16 v[80:83], v[168:171], v[192:195], v[80:83]
	v_mfma_f32_16x16x32_bf16 v[68:71], v[156:159], v[200:203], v[68:71]
	v_mfma_f32_16x16x32_bf16 v[64:67], v[168:171], v[200:203], v[64:67]
	v_mfma_f32_16x16x32_bf16 v[116:119], v[160:163], v[180:183], v[116:119]
	v_mfma_f32_16x16x32_bf16 v[112:115], v[172:175], v[180:183], v[112:115]
	v_mfma_f32_16x16x32_bf16 v[100:103], v[160:163], v[188:191], v[100:103]
	v_mfma_f32_16x16x32_bf16 v[96:99], v[172:175], v[188:191], v[96:99]
	s_barrier
	s_setprio 2
	v_mfma_f32_16x16x32_bf16 v[84:87], v[160:163], v[196:199], v[84:87]
	v_mfma_f32_16x16x32_bf16 v[80:83], v[172:175], v[196:199], v[80:83]
	v_mfma_f32_16x16x32_bf16 v[68:71], v[160:163], v[204:207], v[68:71]
	v_mfma_f32_16x16x32_bf16 v[64:67], v[172:175], v[204:207], v[64:67]
	s_setprio 0
	s_add_i32 s68, s57, s33
	s_mov_b32 m0, s68
	ds_read_b128 v[176:179], v164 offset:16384
	ds_read_b128 v[180:183], v164 offset:17408
	ds_read_b128 v[184:187], v164 offset:18432
	ds_read_b128 v[188:191], v164 offset:19456
	ds_read_b128 v[192:195], v164 offset:20480
	ds_read_b128 v[196:199], v164 offset:21504
	ds_read_b128 v[200:203], v164 offset:22528
	ds_read_b128 v[204:207], v164 offset:23552
	global_load_lds_dwordx4 v166, s[44:45]
	s_add_i32 m0, s68, 0x2000
	s_nop 0
	global_load_lds_dwordx4 v134, s[44:45]
	s_add_i32 s44, s60, s33
	s_mov_b32 m0, s44
	s_nop 0
	global_load_lds_dwordx4 v166, s[46:47]
	s_add_i32 m0, s44, 0x2000
	s_nop 0
	global_load_lds_dwordx4 v134, s[46:47]
	s_mov_b32 m0, s38
	s_nop 0
	global_load_lds_dwordx4 v128, s[42:43]
	s_mov_b32 m0, s39
	s_nop 0
	global_load_lds_dwordx4 v132, s[42:43]
	s_waitcnt vmcnt(8)
	s_waitcnt lgkmcnt(0)
	s_barrier
	s_setprio 1
	s_waitcnt lgkmcnt(0)
	v_mfma_f32_16x16x32_bf16 v[60:63], v[140:143], v[176:179], v[60:63]
	v_mfma_f32_16x16x32_bf16 v[56:59], v[148:151], v[176:179], v[56:59]
	v_mfma_f32_16x16x32_bf16 v[44:47], v[140:143], v[184:187], v[44:47]
	v_mfma_f32_16x16x32_bf16 v[40:43], v[148:151], v[184:187], v[40:43]
	v_mfma_f32_16x16x32_bf16 v[28:31], v[140:143], v[192:195], v[28:31]
	v_mfma_f32_16x16x32_bf16 v[24:27], v[148:151], v[192:195], v[24:27]
	v_mfma_f32_16x16x32_bf16 v[12:15], v[140:143], v[200:203], v[12:15]
	v_mfma_f32_16x16x32_bf16 v[8:11], v[148:151], v[200:203], v[8:11]
	v_mfma_f32_16x16x32_bf16 v[60:63], v[144:147], v[180:183], v[60:63]
	v_mfma_f32_16x16x32_bf16 v[56:59], v[152:155], v[180:183], v[56:59]
	v_mfma_f32_16x16x32_bf16 v[44:47], v[144:147], v[188:191], v[44:47]
	v_mfma_f32_16x16x32_bf16 v[40:43], v[152:155], v[188:191], v[40:43]
	v_mfma_f32_16x16x32_bf16 v[28:31], v[144:147], v[196:199], v[28:31]
	v_mfma_f32_16x16x32_bf16 v[24:27], v[152:155], v[196:199], v[24:27]
	v_mfma_f32_16x16x32_bf16 v[12:15], v[144:147], v[204:207], v[12:15]
	v_mfma_f32_16x16x32_bf16 v[8:11], v[152:155], v[204:207], v[8:11]
	s_setprio 0
	s_setprio 1
	v_mfma_f32_16x16x32_bf16 v[52:55], v[156:159], v[176:179], v[52:55]
	v_mfma_f32_16x16x32_bf16 v[48:51], v[168:171], v[176:179], v[48:51]
	v_mfma_f32_16x16x32_bf16 v[36:39], v[156:159], v[184:187], v[36:39]
	v_mfma_f32_16x16x32_bf16 v[32:35], v[168:171], v[184:187], v[32:35]
	v_mfma_f32_16x16x32_bf16 v[20:23], v[156:159], v[192:195], v[20:23]
	v_mfma_f32_16x16x32_bf16 v[16:19], v[168:171], v[192:195], v[16:19]
	v_mfma_f32_16x16x32_bf16 v[4:7], v[156:159], v[200:203], v[4:7]
	v_mfma_f32_16x16x32_bf16 v[0:3], v[168:171], v[200:203], v[0:3]
	v_mfma_f32_16x16x32_bf16 v[52:55], v[160:163], v[180:183], v[52:55]
	v_mfma_f32_16x16x32_bf16 v[48:51], v[172:175], v[180:183], v[48:51]
	v_mfma_f32_16x16x32_bf16 v[36:39], v[160:163], v[188:191], v[36:39]
	v_mfma_f32_16x16x32_bf16 v[32:35], v[172:175], v[188:191], v[32:35]
	s_barrier
; #define PG8_MMA(ai, bj, At, Bt) do { __builtin_amdgcn_s_setprio(1); _Pragma("unroll") for (int m = 0; m < 4; ++m) _Pragma("unroll") for (int n = 0; n < 2; ++n) _Pragma("unroll") for (int k = 0; k < 2; ++k) \
;         acc[ai][bj][m][n] = __builtin_amdgcn_mfma_f32_16x16x32_bf16(Bt[n][k], At[m][k], acc[ai][bj][m][n], 0, 0, 0); __builtin_amdgcn_s_setprio(0); } while (0)
;     ...
;         { const int tmid = (TSW > 0 && TSW < nt) ? TSW : nt;
;           _Pragma("unroll 1") for (int t = 0; t < tmid; t += 2) { PG8_BODY(PG8_MMA) }
	s_setprio 2
	v_mfma_f32_16x16x32_bf16 v[20:23], v[160:163], v[196:199], v[20:23]
	v_mfma_f32_16x16x32_bf16 v[16:19], v[172:175], v[196:199], v[16:19]
	v_mfma_f32_16x16x32_bf16 v[4:7], v[160:163], v[204:207], v[4:7]
	v_mfma_f32_16x16x32_bf16 v[0:3], v[172:175], v[204:207], v[0:3]
	s_setprio 0
	s_add_i32 s42, 0, 0x18000
	v_add_u32_e32 v130, s42, v129
	s_add_i32 s43, 0, 0x1c000
	ds_read_b128 v[140:143], v130
	ds_read_b128 v[144:147], v130 offset:1024
	ds_read_b128 v[148:151], v130 offset:2048
	ds_read_b128 v[152:155], v130 offset:3072
	v_add_u32_e32 v130, s43, v129
	ds_read_b128 v[156:159], v130
	ds_read_b128 v[160:163], v130 offset:1024
	ds_read_b128 v[168:171], v130 offset:2048
	ds_read_b128 v[172:175], v130 offset:3072
	s_mov_b32 m0, s52
	ds_read_b128 v[176:179], v164 offset:32768
	ds_read_b128 v[180:183], v164 offset:33792
	ds_read_b128 v[184:187], v164 offset:34816
	ds_read_b128 v[188:191], v164 offset:35840
	ds_read_b128 v[192:195], v164 offset:36864
	ds_read_b128 v[196:199], v164 offset:37888
	ds_read_b128 v[200:203], v164 offset:38912
	ds_read_b128 v[204:207], v164 offset:39936
	global_load_lds_dwordx4 v128, s[40:41]
	s_mov_b32 m0, s53
	s_nop 0
	global_load_lds_dwordx4 v132, s[40:41]
	s_waitcnt vmcnt(8)
	s_waitcnt lgkmcnt(0)
	s_barrier
	s_setprio 1
	s_waitcnt lgkmcnt(0)
	v_mfma_f32_16x16x32_bf16 v[124:127], v[140:143], v[176:179], v[124:127]
	v_mfma_f32_16x16x32_bf16 v[120:123], v[148:151], v[176:179], v[120:123]
	v_mfma_f32_16x16x32_bf16 v[108:111], v[140:143], v[184:187], v[108:111]
	v_mfma_f32_16x16x32_bf16 v[104:107], v[148:151], v[184:187], v[104:107]
	v_mfma_f32_16x16x32_bf16 v[92:95], v[140:143], v[192:195], v[92:95]
	v_mfma_f32_16x16x32_bf16 v[88:91], v[148:151], v[192:195], v[88:91]
	v_mfma_f32_16x16x32_bf16 v[76:79], v[140:143], v[200:203], v[76:79]
	v_mfma_f32_16x16x32_bf16 v[72:75], v[148:151], v[200:203], v[72:75]
	v_mfma_f32_16x16x32_bf16 v[124:127], v[144:147], v[180:183], v[124:127]
	v_mfma_f32_16x16x32_bf16 v[120:123], v[152:155], v[180:183], v[120:123]
	v_mfma_f32_16x16x32_bf16 v[108:111], v[144:147], v[188:191], v[108:111]
	v_mfma_f32_16x16x32_bf16 v[104:107], v[152:155], v[188:191], v[104:107]
	v_mfma_f32_16x16x32_bf16 v[92:95], v[144:147], v[196:199], v[92:95]
	v_mfma_f32_16x16x32_bf16 v[88:91], v[152:155], v[196:199], v[88:91]
	v_mfma_f32_16x16x32_bf16 v[76:79], v[144:147], v[204:207], v[76:79]
	v_mfma_f32_16x16x32_bf16 v[72:75], v[152:155], v[204:207], v[72:75]
	s_setprio 0
	s_setprio 1
	v_mfma_f32_16x16x32_bf16 v[116:119], v[156:159], v[176:179], v[116:119]
	v_mfma_f32_16x16x32_bf16 v[112:115], v[168:171], v[176:179], v[112:115]
	v_mfma_f32_16x16x32_bf16 v[100:103], v[156:159], v[184:187], v[100:103]
	v_mfma_f32_16x16x32_bf16 v[96:99], v[168:171], v[184:187], v[96:99]
	v_mfma_f32_16x16x32_bf16 v[84:87], v[156:159], v[192:195], v[84:87]
	v_mfma_f32_16x16x32_bf16 v[80:83], v[168:171], v[192:195], v[80:83]
	v_mfma_f32_16x16x32_bf16 v[68:71], v[156:159], v[200:203], v[68:71]
	v_mfma_f32_16x16x32_bf16 v[64:67], v[168:171], v[200:203], v[64:67]
	v_mfma_f32_16x16x32_bf16 v[116:119], v[160:163], v[180:183], v[116:119]
	v_mfma_f32_16x16x32_bf16 v[112:115], v[172:175], v[180:183], v[112:115]
	v_mfma_f32_16x16x32_bf16 v[100:103], v[160:163], v[188:191], v[100:103]
	v_mfma_f32_16x16x32_bf16 v[96:99], v[172:175], v[188:191], v[96:99]
	s_barrier
	s_setprio 2
	v_mfma_f32_16x16x32_bf16 v[84:87], v[160:163], v[196:199], v[84:87]
	v_mfma_f32_16x16x32_bf16 v[80:83], v[172:175], v[196:199], v[80:83]
	v_mfma_f32_16x16x32_bf16 v[68:71], v[160:163], v[204:207], v[68:71]
	v_mfma_f32_16x16x32_bf16 v[64:67], v[172:175], v[204:207], v[64:67]
	s_setprio 0
	s_add_i32 s40, s42, s33
	s_mov_b32 m0, s40
	ds_read_b128 v[176:179], v164 offset:49152
	ds_read_b128 v[180:183], v164 offset:50176
	ds_read_b128 v[184:187], v164 offset:51200
	ds_read_b128 v[188:191], v164 offset:52224
	ds_read_b128 v[192:195], v164 offset:53248
	ds_read_b128 v[196:199], v164 offset:54272
	ds_read_b128 v[200:203], v164 offset:55296
	ds_read_b128 v[204:207], v164 offset:56320
	global_load_lds_dwordx4 v166, s[36:37]
	s_add_i32 m0, s40, 0x2000
	s_nop 0
	global_load_lds_dwordx4 v134, s[36:37]
	s_add_i32 s36, s43, s33
	s_mov_b32 m0, s36
	s_nop 0
	global_load_lds_dwordx4 v166, s[28:29]
	s_add_i32 m0, s36, 0x2000
	s_nop 0
	global_load_lds_dwordx4 v134, s[28:29]
	s_mov_b32 m0, s14
	s_nop 0
	global_load_lds_dwordx4 v128, s[34:35]
	s_mov_b32 m0, s15
	s_nop 0
	global_load_lds_dwordx4 v132, s[34:35]
	s_waitcnt vmcnt(8)
	s_waitcnt lgkmcnt(0)
	s_barrier
	s_setprio 1
	s_waitcnt lgkmcnt(0)
	v_mfma_f32_16x16x32_bf16 v[60:63], v[140:143], v[176:179], v[60:63]
	v_mfma_f32_16x16x32_bf16 v[56:59], v[148:151], v[176:179], v[56:59]
	v_mfma_f32_16x16x32_bf16 v[44:47], v[140:143], v[184:187], v[44:47]
	v_mfma_f32_16x16x32_bf16 v[40:43], v[148:151], v[184:187], v[40:43]
	v_mfma_f32_16x16x32_bf16 v[28:31], v[140:143], v[192:195], v[28:31]
	v_mfma_f32_16x16x32_bf16 v[24:27], v[148:151], v[192:195], v[24:27]
	v_mfma_f32_16x16x32_bf16 v[12:15], v[140:143], v[200:203], v[12:15]
	v_mfma_f32_16x16x32_bf16 v[8:11], v[148:151], v[200:203], v[8:11]
	v_mfma_f32_16x16x32_bf16 v[60:63], v[144:147], v[180:183], v[60:63]
	v_mfma_f32_16x16x32_bf16 v[56:59], v[152:155], v[180:183], v[56:59]
	v_mfma_f32_16x16x32_bf16 v[44:47], v[144:147], v[188:191], v[44:47]
	v_mfma_f32_16x16x32_bf16 v[40:43], v[152:155], v[188:191], v[40:43]
	v_mfma_f32_16x16x32_bf16 v[28:31], v[144:147], v[196:199], v[28:31]
	v_mfma_f32_16x16x32_bf16 v[24:27], v[152:155], v[196:199], v[24:27]
	v_mfma_f32_16x16x32_bf16 v[12:15], v[144:147], v[204:207], v[12:15]
	v_mfma_f32_16x16x32_bf16 v[8:11], v[152:155], v[204:207], v[8:11]
	s_setprio 0
	s_setprio 1
	v_mfma_f32_16x16x32_bf16 v[52:55], v[156:159], v[176:179], v[52:55]
	v_mfma_f32_16x16x32_bf16 v[48:51], v[168:171], v[176:179], v[48:51]
	v_mfma_f32_16x16x32_bf16 v[36:39], v[156:159], v[184:187], v[36:39]
	v_mfma_f32_16x16x32_bf16 v[32:35], v[168:171], v[184:187], v[32:35]
	v_mfma_f32_16x16x32_bf16 v[20:23], v[156:159], v[192:195], v[20:23]
	v_mfma_f32_16x16x32_bf16 v[16:19], v[168:171], v[192:195], v[16:19]
	v_mfma_f32_16x16x32_bf16 v[4:7], v[156:159], v[200:203], v[4:7]
	v_mfma_f32_16x16x32_bf16 v[0:3], v[168:171], v[200:203], v[0:3]
	v_mfma_f32_16x16x32_bf16 v[52:55], v[160:163], v[180:183], v[52:55]
	v_mfma_f32_16x16x32_bf16 v[48:51], v[172:175], v[180:183], v[48:51]
	v_mfma_f32_16x16x32_bf16 v[36:39], v[160:163], v[188:191], v[36:39]
	v_mfma_f32_16x16x32_bf16 v[32:35], v[172:175], v[188:191], v[32:35]
	s_barrier
	s_setprio 2
	v_mfma_f32_16x16x32_bf16 v[20:23], v[160:163], v[196:199], v[20:23]
	v_mfma_f32_16x16x32_bf16 v[16:19], v[172:175], v[196:199], v[16:19]
	v_mfma_f32_16x16x32_bf16 v[4:7], v[160:163], v[204:207], v[4:7]
	v_mfma_f32_16x16x32_bf16 v[0:3], v[172:175], v[204:207], v[0:3]
	s_setprio 0
	s_add_i32 s67, s67, 2
	s_add_u32 s61, s61, 0x100
	s_addc_u32 s66, s66, 0
	s_cmp_gt_u32 s67, 29
	s_mov_b64 s[28:29], s[30:31]
	s_cbranch_scc0 .LBB0_182
	s_and_b64 vcc, exec, s[16:17]
	s_cbranch_vccz .LBB0_185
	s_barrier

.LBB0_716:
	s_add_u32 s80, s46, 0x100
	s_addc_u32 s81, s47, 0
	s_cmp_eq_u32 s89, 28
	s_cselect_b32 s28, vcc_lo, s80
	s_cselect_b32 s29, s37, s81
	s_cselect_b32 s23, s21, s88
	s_cselect_b32 s22, s86, s87
	s_add_u32 s26, s28, 0x80
	s_addc_u32 s27, s29, 0
	s_add_u32 s66, s22, 0x80
	s_addc_u32 s67, s23, 0
	s_add_u32 s90, s46, 0x80080
	s_addc_u32 s91, s47, 0
	s_add_u32 s52, s28, 0x80000
	s_addc_u32 s53, s29, 0
	s_add_u32 s56, s22, 0x80000
	s_addc_u32 s57, s23, 0
	s_add_u32 s46, s22, 0x80080
	s_addc_u32 s47, s23, 0
	s_add_i32 s92, 0, 0x10000
	v_add_u32_e32 v133, s92, v129
	s_add_i32 s93, 0, 0x14000
	ds_read_b128 v[134:137], v133
	ds_read_b128 v[138:141], v133 offset:1024
	ds_read_b128 v[142:145], v133 offset:2048
	ds_read_b128 v[146:149], v133 offset:3072
	v_add_u32_e32 v133, s93, v129
	ds_read_b128 v[150:153], v133
	ds_read_b128 v[154:157], v133 offset:1024
	ds_read_b128 v[158:161], v133 offset:2048
	ds_read_b128 v[162:165], v133 offset:3072
	s_add_i32 m0, s0, 0xc000
	ds_read_b128 v[166:169], v131
	ds_read_b128 v[170:173], v131 offset:1024
	ds_read_b128 v[174:177], v131 offset:2048
	ds_read_b128 v[178:181], v131 offset:3072
	ds_read_b128 v[182:185], v131 offset:4096
	ds_read_b128 v[186:189], v131 offset:5120
	ds_read_b128 v[202:205], v131 offset:6144
	ds_read_b128 v[206:209], v131 offset:7168
	global_load_lds_dwordx4 v128, s[90:91]
	s_add_i32 m0, s0, 0xe000
	s_nop 0
	global_load_lds_dwordx4 v130, s[90:91]
	s_waitcnt vmcnt(8)
	s_waitcnt lgkmcnt(0)
	s_barrier
	s_setprio 1
	s_waitcnt lgkmcnt(0)
	v_mfma_f32_16x16x32_bf16 v[124:127], v[134:137], v[166:169], v[124:127]
	v_mfma_f32_16x16x32_bf16 v[120:123], v[142:145], v[166:169], v[120:123]
	v_mfma_f32_16x16x32_bf16 v[108:111], v[134:137], v[174:177], v[108:111]
	v_mfma_f32_16x16x32_bf16 v[104:107], v[142:145], v[174:177], v[104:107]
	v_mfma_f32_16x16x32_bf16 v[92:95], v[134:137], v[182:185], v[92:95]
	v_mfma_f32_16x16x32_bf16 v[88:91], v[142:145], v[182:185], v[88:91]
	v_mfma_f32_16x16x32_bf16 v[76:79], v[134:137], v[202:205], v[76:79]
	v_mfma_f32_16x16x32_bf16 v[72:75], v[142:145], v[202:205], v[72:75]
	v_mfma_f32_16x16x32_bf16 v[124:127], v[138:141], v[170:173], v[124:127]
	v_mfma_f32_16x16x32_bf16 v[120:123], v[146:149], v[170:173], v[120:123]
	v_mfma_f32_16x16x32_bf16 v[108:111], v[138:141], v[178:181], v[108:111]
	v_mfma_f32_16x16x32_bf16 v[104:107], v[146:149], v[178:181], v[104:107]
	v_mfma_f32_16x16x32_bf16 v[92:95], v[138:141], v[186:189], v[92:95]
	v_mfma_f32_16x16x32_bf16 v[88:91], v[146:149], v[186:189], v[88:91]
	v_mfma_f32_16x16x32_bf16 v[76:79], v[138:141], v[206:209], v[76:79]
	v_mfma_f32_16x16x32_bf16 v[72:75], v[146:149], v[206:209], v[72:75]
	s_setprio 0
	s_setprio 1
	v_mfma_f32_16x16x32_bf16 v[116:119], v[150:153], v[166:169], v[116:119]
	v_mfma_f32_16x16x32_bf16 v[112:115], v[158:161], v[166:169], v[112:115]
	v_mfma_f32_16x16x32_bf16 v[100:103], v[150:153], v[174:177], v[100:103]
	v_mfma_f32_16x16x32_bf16 v[96:99], v[158:161], v[174:177], v[96:99]
	v_mfma_f32_16x16x32_bf16 v[84:87], v[150:153], v[182:185], v[84:87]
	v_mfma_f32_16x16x32_bf16 v[80:83], v[158:161], v[182:185], v[80:83]
	v_mfma_f32_16x16x32_bf16 v[68:71], v[150:153], v[202:205], v[68:71]
	v_mfma_f32_16x16x32_bf16 v[64:67], v[158:161], v[202:205], v[64:67]
	v_mfma_f32_16x16x32_bf16 v[116:119], v[154:157], v[170:173], v[116:119]
	v_mfma_f32_16x16x32_bf16 v[112:115], v[162:165], v[170:173], v[112:115]
	v_mfma_f32_16x16x32_bf16 v[100:103], v[154:157], v[178:181], v[100:103]
	v_mfma_f32_16x16x32_bf16 v[96:99], v[162:165], v[178:181], v[96:99]
	s_barrier
	s_setprio 2
	v_mfma_f32_16x16x32_bf16 v[84:87], v[154:157], v[186:189], v[84:87]
	v_mfma_f32_16x16x32_bf16 v[80:83], v[162:165], v[186:189], v[80:83]
	v_mfma_f32_16x16x32_bf16 v[68:71], v[154:157], v[206:209], v[68:71]
	v_mfma_f32_16x16x32_bf16 v[64:67], v[162:165], v[206:209], v[64:67]
	s_setprio 0
	s_add_i32 s90, s92, s33
	s_mov_b32 m0, s90
	ds_read_b128 v[166:169], v131 offset:16384
	ds_read_b128 v[170:173], v131 offset:17408
	ds_read_b128 v[174:177], v131 offset:18432
	ds_read_b128 v[178:181], v131 offset:19456
	ds_read_b128 v[182:185], v131 offset:20480
	ds_read_b128 v[186:189], v131 offset:21504
	ds_read_b128 v[202:205], v131 offset:22528
	ds_read_b128 v[206:209], v131 offset:23552
	global_load_lds_dwordx4 v192, s[22:23]
	s_add_i32 m0, s90, 0x2000
	s_nop 0
	global_load_lds_dwordx4 v132, s[22:23]
	s_add_i32 s22, s93, s33
	s_mov_b32 m0, s22
	s_nop 0
	global_load_lds_dwordx4 v192, s[56:57]
	s_add_i32 m0, s22, 0x2000
	s_nop 0
	global_load_lds_dwordx4 v132, s[56:57]
	s_mov_b32 m0, s0
	s_nop 0
	global_load_lds_dwordx4 v128, s[28:29]
	s_mov_b32 m0, s1
	s_nop 0
	global_load_lds_dwordx4 v130, s[28:29]
	s_waitcnt vmcnt(8)
	s_waitcnt lgkmcnt(0)
	s_barrier
	s_setprio 1
	s_waitcnt lgkmcnt(0)
	v_mfma_f32_16x16x32_bf16 v[60:63], v[134:137], v[166:169], v[60:63]
	v_mfma_f32_16x16x32_bf16 v[56:59], v[142:145], v[166:169], v[56:59]
	v_mfma_f32_16x16x32_bf16 v[44:47], v[134:137], v[174:177], v[44:47]
	v_mfma_f32_16x16x32_bf16 v[40:43], v[142:145], v[174:177], v[40:43]
	v_mfma_f32_16x16x32_bf16 v[28:31], v[134:137], v[182:185], v[28:31]
	v_mfma_f32_16x16x32_bf16 v[24:27], v[142:145], v[182:185], v[24:27]
	v_mfma_f32_16x16x32_bf16 v[12:15], v[134:137], v[202:205], v[12:15]
	v_mfma_f32_16x16x32_bf16 v[8:11], v[142:145], v[202:205], v[8:11]
	v_mfma_f32_16x16x32_bf16 v[60:63], v[138:141], v[170:173], v[60:63]
	v_mfma_f32_16x16x32_bf16 v[56:59], v[146:149], v[170:173], v[56:59]
	v_mfma_f32_16x16x32_bf16 v[44:47], v[138:141], v[178:181], v[44:47]
	v_mfma_f32_16x16x32_bf16 v[40:43], v[146:149], v[178:181], v[40:43]
	v_mfma_f32_16x16x32_bf16 v[28:31], v[138:141], v[186:189], v[28:31]
	v_mfma_f32_16x16x32_bf16 v[24:27], v[146:149], v[186:189], v[24:27]
	v_mfma_f32_16x16x32_bf16 v[12:15], v[138:141], v[206:209], v[12:15]
	v_mfma_f32_16x16x32_bf16 v[8:11], v[146:149], v[206:209], v[8:11]
	s_setprio 0
	s_setprio 1
	v_mfma_f32_16x16x32_bf16 v[52:55], v[150:153], v[166:169], v[52:55]
	v_mfma_f32_16x16x32_bf16 v[48:51], v[158:161], v[166:169], v[48:51]
	v_mfma_f32_16x16x32_bf16 v[36:39], v[150:153], v[174:177], v[36:39]
	v_mfma_f32_16x16x32_bf16 v[32:35], v[158:161], v[174:177], v[32:35]
	v_mfma_f32_16x16x32_bf16 v[20:23], v[150:153], v[182:185], v[20:23]
	v_mfma_f32_16x16x32_bf16 v[16:19], v[158:161], v[182:185], v[16:19]
	v_mfma_f32_16x16x32_bf16 v[4:7], v[150:153], v[202:205], v[4:7]
	v_mfma_f32_16x16x32_bf16 v[0:3], v[158:161], v[202:205], v[0:3]
	v_mfma_f32_16x16x32_bf16 v[52:55], v[154:157], v[170:173], v[52:55]
	v_mfma_f32_16x16x32_bf16 v[48:51], v[162:165], v[170:173], v[48:51]
	v_mfma_f32_16x16x32_bf16 v[36:39], v[154:157], v[178:181], v[36:39]
	v_mfma_f32_16x16x32_bf16 v[32:35], v[162:165], v[178:181], v[32:35]
	s_barrier
	s_setprio 2
	v_mfma_f32_16x16x32_bf16 v[20:23], v[154:157], v[186:189], v[20:23]
	v_mfma_f32_16x16x32_bf16 v[16:19], v[162:165], v[186:189], v[16:19]
	v_mfma_f32_16x16x32_bf16 v[4:7], v[154:157], v[206:209], v[4:7]
	v_mfma_f32_16x16x32_bf16 v[0:3], v[162:165], v[206:209], v[0:3]
	s_setprio 0
	s_add_i32 s22, 0, 0x18000
	v_add_u32_e32 v133, s22, v129
	s_add_i32 s23, 0, 0x1c000
	ds_read_b128 v[134:137], v133
	ds_read_b128 v[138:141], v133 offset:1024
	ds_read_b128 v[142:145], v133 offset:2048
	ds_read_b128 v[146:149], v133 offset:3072
	v_add_u32_e32 v133, s23, v129
	ds_read_b128 v[150:153], v133
	ds_read_b128 v[154:157], v133 offset:1024
	ds_read_b128 v[158:161], v133 offset:2048
	ds_read_b128 v[162:165], v133 offset:3072
	s_mov_b32 m0, s34
	ds_read_b128 v[166:169], v131 offset:32768
	ds_read_b128 v[170:173], v131 offset:33792
	ds_read_b128 v[174:177], v131 offset:34816
	ds_read_b128 v[178:181], v131 offset:35840
	ds_read_b128 v[182:185], v131 offset:36864
	ds_read_b128 v[186:189], v131 offset:37888
	ds_read_b128 v[202:205], v131 offset:38912
	ds_read_b128 v[206:209], v131 offset:39936
	global_load_lds_dwordx4 v128, s[52:53]
	s_mov_b32 m0, s35
	s_nop 0
	global_load_lds_dwordx4 v130, s[52:53]
	s_waitcnt vmcnt(8)
	s_waitcnt lgkmcnt(0)
	s_barrier
	s_setprio 1
	s_waitcnt lgkmcnt(0)
	v_mfma_f32_16x16x32_bf16 v[124:127], v[134:137], v[166:169], v[124:127]
	v_mfma_f32_16x16x32_bf16 v[120:123], v[142:145], v[166:169], v[120:123]
	v_mfma_f32_16x16x32_bf16 v[108:111], v[134:137], v[174:177], v[108:111]
	v_mfma_f32_16x16x32_bf16 v[104:107], v[142:145], v[174:177], v[104:107]
	v_mfma_f32_16x16x32_bf16 v[92:95], v[134:137], v[182:185], v[92:95]
	v_mfma_f32_16x16x32_bf16 v[88:91], v[142:145], v[182:185], v[88:91]
	v_mfma_f32_16x16x32_bf16 v[76:79], v[134:137], v[202:205], v[76:79]
	v_mfma_f32_16x16x32_bf16 v[72:75], v[142:145], v[202:205], v[72:75]
	v_mfma_f32_16x16x32_bf16 v[124:127], v[138:141], v[170:173], v[124:127]
	v_mfma_f32_16x16x32_bf16 v[120:123], v[146:149], v[170:173], v[120:123]
	v_mfma_f32_16x16x32_bf16 v[108:111], v[138:141], v[178:181], v[108:111]
	v_mfma_f32_16x16x32_bf16 v[104:107], v[146:149], v[178:181], v[104:107]
	v_mfma_f32_16x16x32_bf16 v[92:95], v[138:141], v[186:189], v[92:95]
	v_mfma_f32_16x16x32_bf16 v[88:91], v[146:149], v[186:189], v[88:91]
	v_mfma_f32_16x16x32_bf16 v[76:79], v[138:141], v[206:209], v[76:79]
	v_mfma_f32_16x16x32_bf16 v[72:75], v[146:149], v[206:209], v[72:75]
	s_setprio 0
	s_setprio 1
	v_mfma_f32_16x16x32_bf16 v[116:119], v[150:153], v[166:169], v[116:119]
	v_mfma_f32_16x16x32_bf16 v[112:115], v[158:161], v[166:169], v[112:115]
	v_mfma_f32_16x16x32_bf16 v[100:103], v[150:153], v[174:177], v[100:103]
	v_mfma_f32_16x16x32_bf16 v[96:99], v[158:161], v[174:177], v[96:99]
	v_mfma_f32_16x16x32_bf16 v[84:87], v[150:153], v[182:185], v[84:87]
	v_mfma_f32_16x16x32_bf16 v[80:83], v[158:161], v[182:185], v[80:83]
	v_mfma_f32_16x16x32_bf16 v[68:71], v[150:153], v[202:205], v[68:71]
	v_mfma_f32_16x16x32_bf16 v[64:67], v[158:161], v[202:205], v[64:67]
	v_mfma_f32_16x16x32_bf16 v[116:119], v[154:157], v[170:173], v[116:119]
	v_mfma_f32_16x16x32_bf16 v[112:115], v[162:165], v[170:173], v[112:115]
	v_mfma_f32_16x16x32_bf16 v[100:103], v[154:157], v[178:181], v[100:103]
	v_mfma_f32_16x16x32_bf16 v[96:99], v[162:165], v[178:181], v[96:99]
	s_barrier
; #define PG8_MMA(ai, bj, At, Bt) do { __builtin_amdgcn_s_setprio(1); _Pragma("unroll") for (int m = 0; m < 4; ++m) _Pragma("unroll") for (int n = 0; n < 2; ++n) _Pragma("unroll") for (int k = 0; k < 2; ++k) \
;         acc[ai][bj][m][n] = __builtin_amdgcn_mfma_f32_16x16x32_bf16(Bt[n][k], At[m][k], acc[ai][bj][m][n], 0, 0, 0); __builtin_amdgcn_s_setprio(0); } while (0)
; #define PG8_MMA8(ai, bj, At, Bt) do { __builtin_amdgcn_s_setprio(1); _Pragma("unroll") for (int m = 0; m < 4; ++m) _Pragma("unroll") for (int n = 0; n < 2; ++n) \
;         acc[ai][bj][m][n] = __builtin_amdgcn_mfma_scale_f32_16x16x128_f8f6f4(PG8_CAT(Bt[n][0], Bt[n][1]), PG8_CAT(At[m][0], At[m][1]), acc[ai][bj][m][n], 0, 0, 0, 0, 0, 0); __builtin_amdgcn_s_setprio(0); } while (0)
; #define PG8_BAR __builtin_amdgcn_s_barrier()
;     ...
;         { const int tmid = (TSW > 0 && TSW < nt) ? TSW : nt;
;           _Pragma("unroll 1") for (int t = 0; t < tmid; t += 2) { PG8_BODY(PG8_MMA) }
;           if constexpr (TSW > 0) { _Pragma("unroll 1") for (int t = tmid; t < nt; t += 2) { PG8_BODY(PG8_MMA8) } } }
;     ...
;         if constexpr (ALIGN_EPI) { if (wr == 0) PG8_BAR; }
	s_setprio 2
	v_mfma_f32_16x16x32_bf16 v[84:87], v[154:157], v[186:189], v[84:87]
	v_mfma_f32_16x16x32_bf16 v[80:83], v[162:165], v[186:189], v[80:83]
	v_mfma_f32_16x16x32_bf16 v[68:71], v[154:157], v[206:209], v[68:71]
	v_mfma_f32_16x16x32_bf16 v[64:67], v[162:165], v[206:209], v[64:67]
	s_setprio 0
	s_add_i32 s22, s22, s33
	s_mov_b32 m0, s22
	ds_read_b128 v[166:169], v131 offset:49152
	ds_read_b128 v[170:173], v131 offset:50176
	ds_read_b128 v[174:177], v131 offset:51200
	ds_read_b128 v[178:181], v131 offset:52224
	ds_read_b128 v[182:185], v131 offset:53248
	ds_read_b128 v[186:189], v131 offset:54272
	ds_read_b128 v[202:205], v131 offset:55296
	ds_read_b128 v[206:209], v131 offset:56320
	global_load_lds_dwordx4 v192, s[66:67]
	s_add_i32 m0, s22, 0x2000
	s_add_i32 s22, s23, s33
	global_load_lds_dwordx4 v132, s[66:67]
	s_mov_b32 m0, s22
	s_nop 0
	global_load_lds_dwordx4 v192, s[46:47]
	s_add_i32 m0, s22, 0x2000
	s_nop 0
	global_load_lds_dwordx4 v132, s[46:47]
	s_mov_b32 m0, s54
	s_nop 0
	global_load_lds_dwordx4 v128, s[26:27]
	s_mov_b32 m0, s55
	s_nop 0
	global_load_lds_dwordx4 v130, s[26:27]
	s_waitcnt vmcnt(8)
	s_waitcnt lgkmcnt(0)
	s_barrier
	s_setprio 1
	s_waitcnt lgkmcnt(0)
	v_mfma_f32_16x16x32_bf16 v[60:63], v[134:137], v[166:169], v[60:63]
	v_mfma_f32_16x16x32_bf16 v[56:59], v[142:145], v[166:169], v[56:59]
	v_mfma_f32_16x16x32_bf16 v[44:47], v[134:137], v[174:177], v[44:47]
	v_mfma_f32_16x16x32_bf16 v[40:43], v[142:145], v[174:177], v[40:43]
	v_mfma_f32_16x16x32_bf16 v[28:31], v[134:137], v[182:185], v[28:31]
	v_mfma_f32_16x16x32_bf16 v[24:27], v[142:145], v[182:185], v[24:27]
	v_mfma_f32_16x16x32_bf16 v[12:15], v[134:137], v[202:205], v[12:15]
	v_mfma_f32_16x16x32_bf16 v[8:11], v[142:145], v[202:205], v[8:11]
	v_mfma_f32_16x16x32_bf16 v[60:63], v[138:141], v[170:173], v[60:63]
	v_mfma_f32_16x16x32_bf16 v[56:59], v[146:149], v[170:173], v[56:59]
	v_mfma_f32_16x16x32_bf16 v[44:47], v[138:141], v[178:181], v[44:47]
	v_mfma_f32_16x16x32_bf16 v[40:43], v[146:149], v[178:181], v[40:43]
	v_mfma_f32_16x16x32_bf16 v[28:31], v[138:141], v[186:189], v[28:31]
	v_mfma_f32_16x16x32_bf16 v[24:27], v[146:149], v[186:189], v[24:27]
	v_mfma_f32_16x16x32_bf16 v[12:15], v[138:141], v[206:209], v[12:15]
	v_mfma_f32_16x16x32_bf16 v[8:11], v[146:149], v[206:209], v[8:11]
	s_setprio 0
	s_setprio 1
	v_mfma_f32_16x16x32_bf16 v[52:55], v[150:153], v[166:169], v[52:55]
	v_mfma_f32_16x16x32_bf16 v[48:51], v[158:161], v[166:169], v[48:51]
	v_mfma_f32_16x16x32_bf16 v[36:39], v[150:153], v[174:177], v[36:39]
	v_mfma_f32_16x16x32_bf16 v[32:35], v[158:161], v[174:177], v[32:35]
	v_mfma_f32_16x16x32_bf16 v[20:23], v[150:153], v[182:185], v[20:23]
	v_mfma_f32_16x16x32_bf16 v[16:19], v[158:161], v[182:185], v[16:19]
	v_mfma_f32_16x16x32_bf16 v[4:7], v[150:153], v[202:205], v[4:7]
	v_mfma_f32_16x16x32_bf16 v[0:3], v[158:161], v[202:205], v[0:3]
	v_mfma_f32_16x16x32_bf16 v[52:55], v[154:157], v[170:173], v[52:55]
	v_mfma_f32_16x16x32_bf16 v[48:51], v[162:165], v[170:173], v[48:51]
	v_mfma_f32_16x16x32_bf16 v[36:39], v[154:157], v[178:181], v[36:39]
	v_mfma_f32_16x16x32_bf16 v[32:35], v[162:165], v[178:181], v[32:35]
	s_barrier
	s_setprio 2
	v_mfma_f32_16x16x32_bf16 v[20:23], v[154:157], v[186:189], v[20:23]
	v_mfma_f32_16x16x32_bf16 v[16:19], v[162:165], v[186:189], v[16:19]
	v_mfma_f32_16x16x32_bf16 v[4:7], v[154:157], v[206:209], v[4:7]
	v_mfma_f32_16x16x32_bf16 v[0:3], v[162:165], v[206:209], v[0:3]
	s_setprio 0
	s_add_i32 s89, s89, 2
	s_add_u32 s87, s87, 0x100
	s_addc_u32 s88, s88, 0
	s_cmp_gt_u32 s89, 29
	s_mov_b64 s[46:47], s[80:81]
	s_cbranch_scc0 .LBB0_716
	s_and_b64 vcc, exec, s[82:83]
	s_cbranch_vccz .LBB0_719
	s_barrier

.LBB0_883:
	s_add_u32 s42, s20, 0x100
	s_addc_u32 s43, s21, 0
	s_cmpk_eq_i32 s89, 0x7c
	s_cselect_b32 s28, s86, s42
	s_cselect_b32 s29, s81, s43
	s_cselect_b32 s23, s37, s88
	s_cselect_b32 s22, s87, vcc_lo
	s_add_u32 s26, s28, 0x80
	s_addc_u32 s27, s29, 0
	s_add_u32 s66, s22, 0x80
	s_addc_u32 s67, s23, 0
	s_add_u32 s90, s20, 0x200080
	s_addc_u32 s91, s21, 0
	s_add_u32 s52, s28, 0x200000
	s_addc_u32 s53, s29, 0
	s_add_u32 s56, s22, 0x200000
	s_addc_u32 s57, s23, 0
	s_add_u32 s20, s22, 0x200080
	s_addc_u32 s21, s23, 0
	s_add_i32 s92, 0, 0x10000
	s_add_i32 s93, 0, 0x14000
	v_add_u32_e32 v140, s92, v203
	v_add_u32_e32 v156, s93, v203
	ds_read_b128 v[128:131], v140
	ds_read_b128 v[132:135], v140 offset:1024
	ds_read_b128 v[136:139], v140 offset:2048
	ds_read_b128 v[140:143], v140 offset:3072
	ds_read_b128 v[144:147], v156
	ds_read_b128 v[148:151], v156 offset:1024
	ds_read_b128 v[152:155], v156 offset:2048
	ds_read_b128 v[156:159], v156 offset:3072
	s_add_i32 m0, s73, 0xc000
	ds_read_b128 v[160:163], v205
	ds_read_b128 v[164:167], v205 offset:1024
	ds_read_b128 v[168:171], v205 offset:2048
	ds_read_b128 v[172:175], v205 offset:3072
	ds_read_b128 v[176:179], v205 offset:4096
	ds_read_b128 v[180:183], v205 offset:5120
	ds_read_b128 v[184:187], v205 offset:6144
	ds_read_b128 v[188:191], v205 offset:7168
	global_load_lds_dwordx4 v202, s[90:91]
	s_add_i32 m0, s73, 0xe000
	s_nop 0
	global_load_lds_dwordx4 v204, s[90:91]
	s_waitcnt vmcnt(8)
	s_waitcnt lgkmcnt(0)
	s_barrier
	s_setprio 1
	s_waitcnt lgkmcnt(0)
	v_mfma_f32_16x16x32_bf16 v[124:127], v[128:131], v[160:163], v[124:127]
	v_mfma_f32_16x16x32_bf16 v[120:123], v[136:139], v[160:163], v[120:123]
	v_mfma_f32_16x16x32_bf16 v[108:111], v[128:131], v[168:171], v[108:111]
	v_mfma_f32_16x16x32_bf16 v[104:107], v[136:139], v[168:171], v[104:107]
	v_mfma_f32_16x16x32_bf16 v[92:95], v[128:131], v[176:179], v[92:95]
	v_mfma_f32_16x16x32_bf16 v[88:91], v[136:139], v[176:179], v[88:91]
	v_mfma_f32_16x16x32_bf16 v[76:79], v[128:131], v[184:187], v[76:79]
	v_mfma_f32_16x16x32_bf16 v[72:75], v[136:139], v[184:187], v[72:75]
	v_mfma_f32_16x16x32_bf16 v[124:127], v[132:135], v[164:167], v[124:127]
	v_mfma_f32_16x16x32_bf16 v[120:123], v[140:143], v[164:167], v[120:123]
	v_mfma_f32_16x16x32_bf16 v[108:111], v[132:135], v[172:175], v[108:111]
	v_mfma_f32_16x16x32_bf16 v[104:107], v[140:143], v[172:175], v[104:107]
	v_mfma_f32_16x16x32_bf16 v[92:95], v[132:135], v[180:183], v[92:95]
	v_mfma_f32_16x16x32_bf16 v[88:91], v[140:143], v[180:183], v[88:91]
	v_mfma_f32_16x16x32_bf16 v[76:79], v[132:135], v[188:191], v[76:79]
	v_mfma_f32_16x16x32_bf16 v[72:75], v[140:143], v[188:191], v[72:75]
	s_setprio 0
	s_setprio 1
	v_mfma_f32_16x16x32_bf16 v[116:119], v[144:147], v[160:163], v[116:119]
	v_mfma_f32_16x16x32_bf16 v[112:115], v[152:155], v[160:163], v[112:115]
	v_mfma_f32_16x16x32_bf16 v[100:103], v[144:147], v[168:171], v[100:103]
	v_mfma_f32_16x16x32_bf16 v[96:99], v[152:155], v[168:171], v[96:99]
	v_mfma_f32_16x16x32_bf16 v[84:87], v[144:147], v[176:179], v[84:87]
	v_mfma_f32_16x16x32_bf16 v[80:83], v[152:155], v[176:179], v[80:83]
	v_mfma_f32_16x16x32_bf16 v[68:71], v[144:147], v[184:187], v[68:71]
	v_mfma_f32_16x16x32_bf16 v[64:67], v[152:155], v[184:187], v[64:67]
	v_mfma_f32_16x16x32_bf16 v[116:119], v[148:151], v[164:167], v[116:119]
	v_mfma_f32_16x16x32_bf16 v[112:115], v[156:159], v[164:167], v[112:115]
	v_mfma_f32_16x16x32_bf16 v[100:103], v[148:151], v[172:175], v[100:103]
	v_mfma_f32_16x16x32_bf16 v[96:99], v[156:159], v[172:175], v[96:99]
	s_barrier
	s_setprio 2
	v_mfma_f32_16x16x32_bf16 v[84:87], v[148:151], v[180:183], v[84:87]
	v_mfma_f32_16x16x32_bf16 v[80:83], v[156:159], v[180:183], v[80:83]
	v_mfma_f32_16x16x32_bf16 v[68:71], v[148:151], v[188:191], v[68:71]
	v_mfma_f32_16x16x32_bf16 v[64:67], v[156:159], v[188:191], v[64:67]
	s_setprio 0
	s_add_i32 s90, s92, s33
	s_mov_b32 m0, s90
	ds_read_b128 v[160:163], v205 offset:16384
	ds_read_b128 v[164:167], v205 offset:17408
	ds_read_b128 v[168:171], v205 offset:18432
	ds_read_b128 v[172:175], v205 offset:19456
	ds_read_b128 v[176:179], v205 offset:20480
	ds_read_b128 v[180:183], v205 offset:21504
	ds_read_b128 v[184:187], v205 offset:22528
	ds_read_b128 v[188:191], v205 offset:23552
	global_load_lds_dwordx4 v192, s[22:23]
	s_add_i32 m0, s90, 0x2000
	s_nop 0
	global_load_lds_dwordx4 v206, s[22:23]
	s_add_i32 s22, s93, s33
	s_mov_b32 m0, s22
	s_nop 0
	global_load_lds_dwordx4 v192, s[56:57]
	s_add_i32 m0, s22, 0x2000
	s_nop 0
	global_load_lds_dwordx4 v206, s[56:57]
	s_mov_b32 m0, s73
	s_nop 0
	global_load_lds_dwordx4 v202, s[28:29]
	s_mov_b32 m0, s34
	s_nop 0
	global_load_lds_dwordx4 v204, s[28:29]
	s_waitcnt vmcnt(8)
	s_waitcnt lgkmcnt(0)
	s_barrier
	s_setprio 1
	s_waitcnt lgkmcnt(0)
	v_mfma_f32_16x16x32_bf16 v[60:63], v[128:131], v[160:163], v[60:63]
	v_mfma_f32_16x16x32_bf16 v[56:59], v[136:139], v[160:163], v[56:59]
	v_mfma_f32_16x16x32_bf16 v[44:47], v[128:131], v[168:171], v[44:47]
	v_mfma_f32_16x16x32_bf16 v[40:43], v[136:139], v[168:171], v[40:43]
	v_mfma_f32_16x16x32_bf16 v[28:31], v[128:131], v[176:179], v[28:31]
	v_mfma_f32_16x16x32_bf16 v[24:27], v[136:139], v[176:179], v[24:27]
	v_mfma_f32_16x16x32_bf16 v[12:15], v[128:131], v[184:187], v[12:15]
	v_mfma_f32_16x16x32_bf16 v[8:11], v[136:139], v[184:187], v[8:11]
	v_mfma_f32_16x16x32_bf16 v[60:63], v[132:135], v[164:167], v[60:63]
	v_mfma_f32_16x16x32_bf16 v[56:59], v[140:143], v[164:167], v[56:59]
	v_mfma_f32_16x16x32_bf16 v[44:47], v[132:135], v[172:175], v[44:47]
	v_mfma_f32_16x16x32_bf16 v[40:43], v[140:143], v[172:175], v[40:43]
	v_mfma_f32_16x16x32_bf16 v[28:31], v[132:135], v[180:183], v[28:31]
	v_mfma_f32_16x16x32_bf16 v[24:27], v[140:143], v[180:183], v[24:27]
	v_mfma_f32_16x16x32_bf16 v[12:15], v[132:135], v[188:191], v[12:15]
	v_mfma_f32_16x16x32_bf16 v[8:11], v[140:143], v[188:191], v[8:11]
	s_setprio 0
	s_setprio 1
	v_mfma_f32_16x16x32_bf16 v[52:55], v[144:147], v[160:163], v[52:55]
	v_mfma_f32_16x16x32_bf16 v[48:51], v[152:155], v[160:163], v[48:51]
	v_mfma_f32_16x16x32_bf16 v[36:39], v[144:147], v[168:171], v[36:39]
	v_mfma_f32_16x16x32_bf16 v[32:35], v[152:155], v[168:171], v[32:35]
	v_mfma_f32_16x16x32_bf16 v[20:23], v[144:147], v[176:179], v[20:23]
	v_mfma_f32_16x16x32_bf16 v[16:19], v[152:155], v[176:179], v[16:19]
	v_mfma_f32_16x16x32_bf16 v[4:7], v[144:147], v[184:187], v[4:7]
	v_mfma_f32_16x16x32_bf16 v[0:3], v[152:155], v[184:187], v[0:3]
	v_mfma_f32_16x16x32_bf16 v[52:55], v[148:151], v[164:167], v[52:55]
	v_mfma_f32_16x16x32_bf16 v[48:51], v[156:159], v[164:167], v[48:51]
	v_mfma_f32_16x16x32_bf16 v[36:39], v[148:151], v[172:175], v[36:39]
	v_mfma_f32_16x16x32_bf16 v[32:35], v[156:159], v[172:175], v[32:35]
	s_barrier
	s_setprio 2
	v_mfma_f32_16x16x32_bf16 v[20:23], v[148:151], v[180:183], v[20:23]
	v_mfma_f32_16x16x32_bf16 v[16:19], v[156:159], v[180:183], v[16:19]
	v_mfma_f32_16x16x32_bf16 v[4:7], v[148:151], v[188:191], v[4:7]
	v_mfma_f32_16x16x32_bf16 v[0:3], v[156:159], v[188:191], v[0:3]
	s_setprio 0
	s_add_i32 s22, 0, 0x18000
	s_add_i32 s23, 0, 0x1c000
	v_add_u32_e32 v140, s22, v203
	v_add_u32_e32 v156, s23, v203
	ds_read_b128 v[128:131], v140
	ds_read_b128 v[132:135], v140 offset:1024
	ds_read_b128 v[136:139], v140 offset:2048
	ds_read_b128 v[140:143], v140 offset:3072
	ds_read_b128 v[144:147], v156
	ds_read_b128 v[148:151], v156 offset:1024
	ds_read_b128 v[152:155], v156 offset:2048
	ds_read_b128 v[156:159], v156 offset:3072
	s_mov_b32 m0, s35
	ds_read_b128 v[160:163], v205 offset:32768
	ds_read_b128 v[164:167], v205 offset:33792
	ds_read_b128 v[168:171], v205 offset:34816
	ds_read_b128 v[172:175], v205 offset:35840
	ds_read_b128 v[176:179], v205 offset:36864
	ds_read_b128 v[180:183], v205 offset:37888
	ds_read_b128 v[184:187], v205 offset:38912
	ds_read_b128 v[188:191], v205 offset:39936
	global_load_lds_dwordx4 v202, s[52:53]
	s_mov_b32 m0, s0
	s_nop 0
	global_load_lds_dwordx4 v204, s[52:53]
	s_waitcnt vmcnt(8)
	s_waitcnt lgkmcnt(0)
	s_barrier
	s_setprio 1
	s_waitcnt lgkmcnt(0)
	v_mfma_f32_16x16x32_bf16 v[124:127], v[128:131], v[160:163], v[124:127]
	v_mfma_f32_16x16x32_bf16 v[120:123], v[136:139], v[160:163], v[120:123]
	v_mfma_f32_16x16x32_bf16 v[108:111], v[128:131], v[168:171], v[108:111]
	v_mfma_f32_16x16x32_bf16 v[104:107], v[136:139], v[168:171], v[104:107]
	v_mfma_f32_16x16x32_bf16 v[92:95], v[128:131], v[176:179], v[92:95]
	v_mfma_f32_16x16x32_bf16 v[88:91], v[136:139], v[176:179], v[88:91]
	v_mfma_f32_16x16x32_bf16 v[76:79], v[128:131], v[184:187], v[76:79]
	v_mfma_f32_16x16x32_bf16 v[72:75], v[136:139], v[184:187], v[72:75]
	v_mfma_f32_16x16x32_bf16 v[124:127], v[132:135], v[164:167], v[124:127]
	v_mfma_f32_16x16x32_bf16 v[120:123], v[140:143], v[164:167], v[120:123]
	v_mfma_f32_16x16x32_bf16 v[108:111], v[132:135], v[172:175], v[108:111]
	v_mfma_f32_16x16x32_bf16 v[104:107], v[140:143], v[172:175], v[104:107]
	v_mfma_f32_16x16x32_bf16 v[92:95], v[132:135], v[180:183], v[92:95]
	v_mfma_f32_16x16x32_bf16 v[88:91], v[140:143], v[180:183], v[88:91]
	v_mfma_f32_16x16x32_bf16 v[76:79], v[132:135], v[188:191], v[76:79]
	v_mfma_f32_16x16x32_bf16 v[72:75], v[140:143], v[188:191], v[72:75]
	s_setprio 0
	s_setprio 1
	v_mfma_f32_16x16x32_bf16 v[116:119], v[144:147], v[160:163], v[116:119]
	v_mfma_f32_16x16x32_bf16 v[112:115], v[152:155], v[160:163], v[112:115]
	v_mfma_f32_16x16x32_bf16 v[100:103], v[144:147], v[168:171], v[100:103]
	v_mfma_f32_16x16x32_bf16 v[96:99], v[152:155], v[168:171], v[96:99]
	v_mfma_f32_16x16x32_bf16 v[84:87], v[144:147], v[176:179], v[84:87]
	v_mfma_f32_16x16x32_bf16 v[80:83], v[152:155], v[176:179], v[80:83]
	v_mfma_f32_16x16x32_bf16 v[68:71], v[144:147], v[184:187], v[68:71]
	v_mfma_f32_16x16x32_bf16 v[64:67], v[152:155], v[184:187], v[64:67]
	v_mfma_f32_16x16x32_bf16 v[116:119], v[148:151], v[164:167], v[116:119]
	v_mfma_f32_16x16x32_bf16 v[112:115], v[156:159], v[164:167], v[112:115]
	v_mfma_f32_16x16x32_bf16 v[100:103], v[148:151], v[172:175], v[100:103]
	v_mfma_f32_16x16x32_bf16 v[96:99], v[156:159], v[172:175], v[96:99]
	s_barrier
; #define PG8_MMA(ai, bj, At, Bt) do { __builtin_amdgcn_s_setprio(1); _Pragma("unroll") for (int m = 0; m < 4; ++m) _Pragma("unroll") for (int n = 0; n < 2; ++n) _Pragma("unroll") for (int k = 0; k < 2; ++k) \
;         acc[ai][bj][m][n] = __builtin_amdgcn_mfma_f32_16x16x32_bf16(Bt[n][k], At[m][k], acc[ai][bj][m][n], 0, 0, 0); __builtin_amdgcn_s_setprio(0); } while (0)
; #define PG8_MMA8(ai, bj, At, Bt) do { __builtin_amdgcn_s_setprio(1); _Pragma("unroll") for (int m = 0; m < 4; ++m) _Pragma("unroll") for (int n = 0; n < 2; ++n) \
;         acc[ai][bj][m][n] = __builtin_amdgcn_mfma_scale_f32_16x16x128_f8f6f4(PG8_CAT(Bt[n][0], Bt[n][1]), PG8_CAT(At[m][0], At[m][1]), acc[ai][bj][m][n], 0, 0, 0, 0, 0, 0); __builtin_amdgcn_s_setprio(0); } while (0)
; #define PG8_BAR __builtin_amdgcn_s_barrier()
;     ...
;         { const int tmid = (TSW > 0 && TSW < nt) ? TSW : nt;
;           _Pragma("unroll 1") for (int t = 0; t < tmid; t += 2) { PG8_BODY(PG8_MMA) }
;           if constexpr (TSW > 0) { _Pragma("unroll 1") for (int t = tmid; t < nt; t += 2) { PG8_BODY(PG8_MMA8) } } }
;     ...
;         if constexpr (ALIGN_EPI) { if (wr == 0) PG8_BAR; }
	s_setprio 2
	v_mfma_f32_16x16x32_bf16 v[84:87], v[148:151], v[180:183], v[84:87]
	v_mfma_f32_16x16x32_bf16 v[80:83], v[156:159], v[180:183], v[80:83]
	v_mfma_f32_16x16x32_bf16 v[68:71], v[148:151], v[188:191], v[68:71]
	v_mfma_f32_16x16x32_bf16 v[64:67], v[156:159], v[188:191], v[64:67]
	s_setprio 0
	s_add_i32 s22, s22, s33
	s_mov_b32 m0, s22
	ds_read_b128 v[160:163], v205 offset:49152
	ds_read_b128 v[164:167], v205 offset:50176
	ds_read_b128 v[168:171], v205 offset:51200
	ds_read_b128 v[172:175], v205 offset:52224
	ds_read_b128 v[176:179], v205 offset:53248
	ds_read_b128 v[180:183], v205 offset:54272
	ds_read_b128 v[184:187], v205 offset:55296
	ds_read_b128 v[188:191], v205 offset:56320
	global_load_lds_dwordx4 v192, s[66:67]
	s_add_i32 m0, s22, 0x2000
	s_add_i32 s22, s23, s33
	global_load_lds_dwordx4 v206, s[66:67]
	s_mov_b32 m0, s22
	s_nop 0
	global_load_lds_dwordx4 v192, s[20:21]
	s_add_i32 m0, s22, 0x2000
	s_nop 0
	global_load_lds_dwordx4 v206, s[20:21]
	s_mov_b32 m0, s1
	s_nop 0
	global_load_lds_dwordx4 v202, s[26:27]
	s_mov_b32 m0, s54
	s_nop 0
	global_load_lds_dwordx4 v204, s[26:27]
	s_waitcnt vmcnt(8)
	s_waitcnt lgkmcnt(0)
	s_barrier
	s_setprio 1
	s_waitcnt lgkmcnt(0)
	v_mfma_f32_16x16x32_bf16 v[60:63], v[128:131], v[160:163], v[60:63]
	v_mfma_f32_16x16x32_bf16 v[56:59], v[136:139], v[160:163], v[56:59]
	v_mfma_f32_16x16x32_bf16 v[44:47], v[128:131], v[168:171], v[44:47]
	v_mfma_f32_16x16x32_bf16 v[40:43], v[136:139], v[168:171], v[40:43]
	v_mfma_f32_16x16x32_bf16 v[28:31], v[128:131], v[176:179], v[28:31]
	v_mfma_f32_16x16x32_bf16 v[24:27], v[136:139], v[176:179], v[24:27]
	v_mfma_f32_16x16x32_bf16 v[12:15], v[128:131], v[184:187], v[12:15]
	v_mfma_f32_16x16x32_bf16 v[8:11], v[136:139], v[184:187], v[8:11]
	v_mfma_f32_16x16x32_bf16 v[60:63], v[132:135], v[164:167], v[60:63]
	v_mfma_f32_16x16x32_bf16 v[56:59], v[140:143], v[164:167], v[56:59]
	v_mfma_f32_16x16x32_bf16 v[44:47], v[132:135], v[172:175], v[44:47]
	v_mfma_f32_16x16x32_bf16 v[40:43], v[140:143], v[172:175], v[40:43]
	v_mfma_f32_16x16x32_bf16 v[28:31], v[132:135], v[180:183], v[28:31]
	v_mfma_f32_16x16x32_bf16 v[24:27], v[140:143], v[180:183], v[24:27]
	v_mfma_f32_16x16x32_bf16 v[12:15], v[132:135], v[188:191], v[12:15]
	v_mfma_f32_16x16x32_bf16 v[8:11], v[140:143], v[188:191], v[8:11]
	s_setprio 0
	s_setprio 1
	v_mfma_f32_16x16x32_bf16 v[52:55], v[144:147], v[160:163], v[52:55]
	v_mfma_f32_16x16x32_bf16 v[48:51], v[152:155], v[160:163], v[48:51]
	v_mfma_f32_16x16x32_bf16 v[36:39], v[144:147], v[168:171], v[36:39]
	v_mfma_f32_16x16x32_bf16 v[32:35], v[152:155], v[168:171], v[32:35]
	v_mfma_f32_16x16x32_bf16 v[20:23], v[144:147], v[176:179], v[20:23]
	v_mfma_f32_16x16x32_bf16 v[16:19], v[152:155], v[176:179], v[16:19]
	v_mfma_f32_16x16x32_bf16 v[4:7], v[144:147], v[184:187], v[4:7]
	v_mfma_f32_16x16x32_bf16 v[0:3], v[152:155], v[184:187], v[0:3]
	v_mfma_f32_16x16x32_bf16 v[52:55], v[148:151], v[164:167], v[52:55]
	v_mfma_f32_16x16x32_bf16 v[48:51], v[156:159], v[164:167], v[48:51]
	v_mfma_f32_16x16x32_bf16 v[36:39], v[148:151], v[172:175], v[36:39]
	v_mfma_f32_16x16x32_bf16 v[32:35], v[156:159], v[172:175], v[32:35]
	s_barrier
	s_setprio 2
	v_mfma_f32_16x16x32_bf16 v[20:23], v[148:151], v[180:183], v[20:23]
	v_mfma_f32_16x16x32_bf16 v[16:19], v[156:159], v[180:183], v[16:19]
	v_mfma_f32_16x16x32_bf16 v[4:7], v[148:151], v[188:191], v[4:7]
	v_mfma_f32_16x16x32_bf16 v[0:3], v[156:159], v[188:191], v[0:3]
	s_setprio 0
	s_add_i32 s89, s89, 2
	s_add_u32 vcc_lo, vcc_lo, 0x100
	s_addc_u32 s88, s88, 0
	s_cmpk_gt_u32 s89, 0x7d
	s_mov_b64 s[20:21], s[42:43]
	s_cbranch_scc0 .LBB0_883
	s_and_b64 vcc, exec, s[82:83]
	s_cbranch_vccz .LBB0_886
	s_barrier
